# v19_nodesync
# baseline (speedup 1.0000x reference)
; __device__ __forceinline__ void gemm_phase(const Params& P, const GArgs& ga, int wid_s, int first, int stride) {
;   const int nN = ga.N / BM;
;   const int nM = ga.split ? NP / BM : NTOK / BM;
;   const int nwg = nM * nN;
;   const int nitems = ga.split ? nwg + (NS / BM) * nN * 8 : nwg;
;   const int nkt_all = ga.K / BK;
;   for (int t = first; t < nitems; t += stride) {
.LBB0_288:
	s_and_b64 s[8:9], s[4:5], exec
	s_cselect_b32 s41, 0x44, 64
	s_mul_i32 s54, s78, s41
	s_lshl_b32 s8, s78, 5
	s_add_i32 s8, s54, s8
	s_and_b64 s[4:5], s[4:5], exec
	s_cselect_b32 s91, s54, s8
	s_cmp_ge_i32 s59, s91
	s_cbranch_scc1 .LBB0_261
	v_cvt_f32_u32_e32 v0, s78
	s_lshl_b32 s44, s78, 2
	v_cvt_f32_u32_e32 v2, s44
	s_xor_b64 s[34:35], s[0:1], -1
	v_rcp_iflag_f32_e32 v0, v0
	s_sub_i32 s0, 0, s78
	v_rcp_iflag_f32_e32 v2, v2
	s_mov_b64 s[36:37], s[84:85]
	v_mul_f32_e32 v0, 0x4f7ffffe, v0
	v_cvt_u32_f32_e32 v0, v0
	s_xor_b64 s[96:97], s[6:7], -1
	s_lshr_b32 s76, s93, 6
	s_lshr_b32 s42, s93, 9
	v_readfirstlane_b32 s1, v0
	v_mul_f32_e32 v0, 0x4f7ffffe, v2
	v_cvt_u32_f32_e32 v0, v0
	s_mul_i32 s0, s0, s1
	s_mul_hi_u32 s0, s1, s0
	s_add_i32 s45, s1, s0
	s_sub_i32 s0, 0, s44
	v_readfirstlane_b32 s1, v0
	s_mul_i32 s0, s0, s1
	s_mul_hi_u32 s0, s1, s0
	s_lshr_b32 s43, s54, 3
	s_mov_b32 s21, s20
	s_add_i32 s46, s1, s0
	s_lshl_b32 s47, s93, 7
	s_lshl_b32 s48, s93, 1
	s_lshl_b32 s49, s93, 9
	s_bitcmp1_b32 s59, 3
	s_cbranch_scc0 .Ldsy_skip
	s_memrealtime s[0:1]
	s_waitcnt lgkmcnt(0)
	s_add_u32 s0, s0, 0
	s_addc_u32 s1, s1, 0
